# in-proj start offsets by class: B (two main units + V^T) about 8 us, C (one main unit + two V^T) about 12 us after class A
# speedup vs baseline: 1.0242x; 1.0059x over previous
.LBB0_439:
	s_andn2_b64 vcc, exec, s[90:91]
	s_cbranch_vccnz .LBB0_590
	v_readlane_b32 s6, v236, 46
	s_mul_i32 s0, s6, 0x1b00000
	s_mul_hi_i32 s1, s6, 0x1b00000
	s_add_u32 s0, s10, s0
	s_addc_u32 s1, s11, s1
	v_readlane_b32 s7, v236, 47
	s_add_u32 s16, s10, 0xa000000
	s_addc_u32 s17, s11, 0
	s_lshl_b64 s[14:15], s[6:7], 21
	s_add_u32 s2, s10, s14
	s_addc_u32 s18, s11, s15
	s_add_u32 s40, s2, 0x9000000
	s_addc_u32 s41, s18, 0
	s_lshl_b32 s14, s6, 9
	s_ashr_i32 s15, s14, 31
	s_lshl_b64 s[14:15], s[14:15], 1
	s_add_u32 s14, s10, s14
	s_addc_u32 s15, s11, s15
	s_add_u32 s42, s14, 0xa100000
	s_addc_u32 s43, s15, 0
	s_add_u32 s44, s0, 0x1500000
	s_addc_u32 s45, s1, 0
	s_add_u32 s46, s2, 0x9800000
	s_addc_u32 s47, s18, 0
	s_lshl_b64 s[14:15], s[6:7], 18
	s_add_u32 s2, s10, s14
	s_addc_u32 s14, s11, s15
	s_add_u32 s48, s2, 0xa200000
	s_mov_b32 s35, s30
	s_mov_b32 s30, s63
	s_mov_b32 s58, s62
	s_mov_b32 s33, s29
	s_mov_b64 s[28:29], s[84:85]
	s_mov_b32 s31, s87
	s_addc_u32 s49, s14, 0
	v_readlane_b32 s86, v237, 57
	s_nop 0
	s_cmp_lt_u32 s86, 0x68
	s_cbranch_scc1 .Lk0_nosleep
	s_sleep 127
	s_sleep 127
	s_cmp_lt_u32 s86, 0xd0
	s_cbranch_scc1 .Lk0_nosleep
	s_sleep 127
